# v97 + gemm_in epilogues (phases 1, 9): bf16 stores of sub-tiles j=2,3 of each row group merged into one 16-byte store via v_permlane16_swap
# speedup vs baseline: 1.0172x; 1.0000x over previous
.LBB0_116:
	v_mov_b32_e32 v157, v156
	v_mov_b32_e32 v158, v156
	v_mov_b32_e32 v159, v156
	v_pk_mul_f32 v[160:161], v[124:125], v[158:159]
	v_pk_mul_f32 v[162:163], v[122:123], v[156:157]
	v_pk_mul_f32 v[164:165], v[120:121], v[158:159]
	v_pk_mul_f32 v[168:169], v[118:119], v[156:157]
	v_pk_mul_f32 v[158:159], v[116:117], v[158:159]
	v_pk_mul_f32 v[156:157], v[114:115], v[156:157]
	v_cvt_pk_bf16_f32 v162, v162, v163
	v_cvt_pk_bf16_f32 v163, v160, v161
	v_lshl_add_u64 v[160:161], v[154:155], 0, v[132:133]
	flat_store_dwordx2 v[160:161], v[162:163] offset:32
	v_cvt_pk_bf16_f32 v162, v168, v169
	v_cvt_pk_bf16_f32 v163, v164, v165
	v_cvt_pk_bf16_f32 v156, v156, v157
	v_cvt_pk_bf16_f32 v157, v158, v159
	v_mov_b32_e32 v230, v162
	v_mov_b32_e32 v231, v163
	v_mov_b32_e32 v232, v156
	v_mov_b32_e32 v233, v157
	v_mbcnt_lo_u32_b32 v236, -1, 0
	v_mbcnt_hi_u32_b32 v236, -1, v236
	v_and_b32_e32 v236, 16, v236
	v_lshrrev_b32_e32 v234, 1, v236
	v_add_u32_e32 v236, v236, v234
	v_mov_b32_e32 v237, 0
	v_lshl_add_u64 v[234:235], v[160:161], 0, v[236:237]
	v_permlane16_swap_b32_e32 v230, v232
	v_permlane16_swap_b32_e32 v231, v233
	global_store_dwordx4 v[234:235], v[230:233], off offset:64
	s_nop 1

.LBB0_120:
	v_mov_b32_e32 v157, v156
	v_mov_b32_e32 v158, v156
	v_mov_b32_e32 v159, v156
	v_pk_mul_f32 v[160:161], v[108:109], v[158:159]
	v_pk_mul_f32 v[162:163], v[106:107], v[156:157]
	v_pk_mul_f32 v[164:165], v[104:105], v[158:159]
	v_pk_mul_f32 v[168:169], v[102:103], v[156:157]
	v_pk_mul_f32 v[158:159], v[100:101], v[158:159]
	v_pk_mul_f32 v[156:157], v[98:99], v[156:157]
	v_cvt_pk_bf16_f32 v162, v162, v163
	v_cvt_pk_bf16_f32 v163, v160, v161
	v_lshl_add_u64 v[160:161], v[154:155], 0, v[132:133]
	flat_store_dwordx2 v[160:161], v[162:163] offset:32
	v_cvt_pk_bf16_f32 v162, v168, v169
	v_cvt_pk_bf16_f32 v163, v164, v165
	v_cvt_pk_bf16_f32 v156, v156, v157
	v_cvt_pk_bf16_f32 v157, v158, v159
	v_mov_b32_e32 v230, v162
	v_mov_b32_e32 v231, v163
	v_mov_b32_e32 v232, v156
	v_mov_b32_e32 v233, v157
	v_mbcnt_lo_u32_b32 v236, -1, 0
	v_mbcnt_hi_u32_b32 v236, -1, v236
	v_and_b32_e32 v236, 16, v236
	v_lshrrev_b32_e32 v234, 1, v236
	v_add_u32_e32 v236, v236, v234
	v_mov_b32_e32 v237, 0
	v_lshl_add_u64 v[234:235], v[160:161], 0, v[236:237]
	v_permlane16_swap_b32_e32 v230, v232
	v_permlane16_swap_b32_e32 v231, v233
	global_store_dwordx4 v[234:235], v[230:233], off offset:64
	s_nop 1

.LBB0_124:
	v_mov_b32_e32 v157, v156
	v_mov_b32_e32 v158, v156
	v_mov_b32_e32 v159, v156
	v_pk_mul_f32 v[160:161], v[92:93], v[158:159]
	v_pk_mul_f32 v[162:163], v[90:91], v[156:157]
	v_pk_mul_f32 v[164:165], v[88:89], v[158:159]
	v_pk_mul_f32 v[168:169], v[86:87], v[156:157]
	v_pk_mul_f32 v[158:159], v[84:85], v[158:159]
	v_pk_mul_f32 v[156:157], v[82:83], v[156:157]
	v_cvt_pk_bf16_f32 v162, v162, v163
	v_cvt_pk_bf16_f32 v163, v160, v161
	v_lshl_add_u64 v[160:161], v[154:155], 0, v[132:133]
	flat_store_dwordx2 v[160:161], v[162:163] offset:32
	v_cvt_pk_bf16_f32 v162, v168, v169
	v_cvt_pk_bf16_f32 v163, v164, v165
	v_cvt_pk_bf16_f32 v156, v156, v157
	v_cvt_pk_bf16_f32 v157, v158, v159
	v_mov_b32_e32 v230, v162
	v_mov_b32_e32 v231, v163
	v_mov_b32_e32 v232, v156
	v_mov_b32_e32 v233, v157
	v_mbcnt_lo_u32_b32 v236, -1, 0
	v_mbcnt_hi_u32_b32 v236, -1, v236
	v_and_b32_e32 v236, 16, v236
	v_lshrrev_b32_e32 v234, 1, v236
	v_add_u32_e32 v236, v236, v234
	v_mov_b32_e32 v237, 0
	v_lshl_add_u64 v[234:235], v[160:161], 0, v[236:237]
	v_permlane16_swap_b32_e32 v230, v232
	v_permlane16_swap_b32_e32 v231, v233
	global_store_dwordx4 v[234:235], v[230:233], off offset:64
	s_nop 1

.LBB0_128:
	v_mov_b32_e32 v157, v156
	v_mov_b32_e32 v158, v156
	v_mov_b32_e32 v159, v156
	v_pk_mul_f32 v[160:161], v[76:77], v[158:159]
	v_pk_mul_f32 v[162:163], v[74:75], v[156:157]
	v_pk_mul_f32 v[164:165], v[72:73], v[158:159]
	v_pk_mul_f32 v[168:169], v[70:71], v[156:157]
	v_pk_mul_f32 v[158:159], v[68:69], v[158:159]
	v_pk_mul_f32 v[156:157], v[66:67], v[156:157]
	v_cvt_pk_bf16_f32 v162, v162, v163
	v_cvt_pk_bf16_f32 v163, v160, v161
	v_lshl_add_u64 v[160:161], v[154:155], 0, v[132:133]
	flat_store_dwordx2 v[160:161], v[162:163] offset:32
	v_cvt_pk_bf16_f32 v162, v168, v169
	v_cvt_pk_bf16_f32 v163, v164, v165
	v_cvt_pk_bf16_f32 v156, v156, v157
	v_cvt_pk_bf16_f32 v157, v158, v159
	v_mov_b32_e32 v230, v162
	v_mov_b32_e32 v231, v163
	v_mov_b32_e32 v232, v156
	v_mov_b32_e32 v233, v157
	v_mbcnt_lo_u32_b32 v236, -1, 0
	v_mbcnt_hi_u32_b32 v236, -1, v236
	v_and_b32_e32 v236, 16, v236
	v_lshrrev_b32_e32 v234, 1, v236
	v_add_u32_e32 v236, v236, v234
	v_mov_b32_e32 v237, 0
	v_lshl_add_u64 v[234:235], v[160:161], 0, v[236:237]
	v_permlane16_swap_b32_e32 v230, v232
	v_permlane16_swap_b32_e32 v231, v233
	global_store_dwordx4 v[234:235], v[230:233], off offset:64
	s_nop 1

.LBB0_132:
	v_mov_b32_e32 v157, v156
	v_mov_b32_e32 v158, v156
	v_mov_b32_e32 v159, v156
	v_pk_mul_f32 v[160:161], v[60:61], v[158:159]
	v_pk_mul_f32 v[162:163], v[58:59], v[156:157]
	v_pk_mul_f32 v[164:165], v[56:57], v[158:159]
	v_pk_mul_f32 v[168:169], v[54:55], v[156:157]
	v_pk_mul_f32 v[158:159], v[52:53], v[158:159]
	v_pk_mul_f32 v[156:157], v[50:51], v[156:157]
	v_cvt_pk_bf16_f32 v162, v162, v163
	v_cvt_pk_bf16_f32 v163, v160, v161
	v_lshl_add_u64 v[160:161], v[154:155], 0, v[132:133]
	flat_store_dwordx2 v[160:161], v[162:163] offset:32
	v_cvt_pk_bf16_f32 v162, v168, v169
	v_cvt_pk_bf16_f32 v163, v164, v165
	v_cvt_pk_bf16_f32 v156, v156, v157
	v_cvt_pk_bf16_f32 v157, v158, v159
	v_mov_b32_e32 v230, v162
	v_mov_b32_e32 v231, v163
	v_mov_b32_e32 v232, v156
	v_mov_b32_e32 v233, v157
	v_mbcnt_lo_u32_b32 v236, -1, 0
	v_mbcnt_hi_u32_b32 v236, -1, v236
	v_and_b32_e32 v236, 16, v236
	v_lshrrev_b32_e32 v234, 1, v236
	v_add_u32_e32 v236, v236, v234
	v_mov_b32_e32 v237, 0
	v_lshl_add_u64 v[234:235], v[160:161], 0, v[236:237]
	v_permlane16_swap_b32_e32 v230, v232
	v_permlane16_swap_b32_e32 v231, v233
	global_store_dwordx4 v[234:235], v[230:233], off offset:64
	s_nop 1

.LBB0_136:
	v_mov_b32_e32 v157, v156
	v_mov_b32_e32 v158, v156
	v_mov_b32_e32 v159, v156
	v_pk_mul_f32 v[160:161], v[44:45], v[158:159]
	v_pk_mul_f32 v[162:163], v[42:43], v[156:157]
	v_pk_mul_f32 v[164:165], v[40:41], v[158:159]
	v_pk_mul_f32 v[168:169], v[38:39], v[156:157]
	v_pk_mul_f32 v[158:159], v[36:37], v[158:159]
	v_pk_mul_f32 v[156:157], v[34:35], v[156:157]
	v_cvt_pk_bf16_f32 v162, v162, v163
	v_cvt_pk_bf16_f32 v163, v160, v161
	v_lshl_add_u64 v[160:161], v[154:155], 0, v[132:133]
	flat_store_dwordx2 v[160:161], v[162:163] offset:32
	v_cvt_pk_bf16_f32 v162, v168, v169
	v_cvt_pk_bf16_f32 v163, v164, v165
	v_cvt_pk_bf16_f32 v156, v156, v157
	v_cvt_pk_bf16_f32 v157, v158, v159
	v_mov_b32_e32 v230, v162
	v_mov_b32_e32 v231, v163
	v_mov_b32_e32 v232, v156
	v_mov_b32_e32 v233, v157
	v_mbcnt_lo_u32_b32 v236, -1, 0
	v_mbcnt_hi_u32_b32 v236, -1, v236
	v_and_b32_e32 v236, 16, v236
	v_lshrrev_b32_e32 v234, 1, v236
	v_add_u32_e32 v236, v236, v234
	v_mov_b32_e32 v237, 0
	v_lshl_add_u64 v[234:235], v[160:161], 0, v[236:237]
	v_permlane16_swap_b32_e32 v230, v232
	v_permlane16_swap_b32_e32 v231, v233
	global_store_dwordx4 v[234:235], v[230:233], off offset:64
	s_nop 1

.LBB0_140:
	v_mov_b32_e32 v157, v156
	v_mov_b32_e32 v158, v156
	v_mov_b32_e32 v159, v156
	v_pk_mul_f32 v[160:161], v[28:29], v[158:159]
	v_pk_mul_f32 v[162:163], v[26:27], v[156:157]
	v_pk_mul_f32 v[164:165], v[24:25], v[158:159]
	v_pk_mul_f32 v[168:169], v[22:23], v[156:157]
	v_pk_mul_f32 v[158:159], v[20:21], v[158:159]
	v_pk_mul_f32 v[156:157], v[18:19], v[156:157]
	v_cvt_pk_bf16_f32 v162, v162, v163
	v_cvt_pk_bf16_f32 v163, v160, v161
	v_lshl_add_u64 v[160:161], v[154:155], 0, v[132:133]
	flat_store_dwordx2 v[160:161], v[162:163] offset:32
	v_cvt_pk_bf16_f32 v162, v168, v169
	v_cvt_pk_bf16_f32 v163, v164, v165
	v_cvt_pk_bf16_f32 v156, v156, v157
	v_cvt_pk_bf16_f32 v157, v158, v159
	v_mov_b32_e32 v230, v162
	v_mov_b32_e32 v231, v163
	v_mov_b32_e32 v232, v156
	v_mov_b32_e32 v233, v157
	v_mbcnt_lo_u32_b32 v236, -1, 0
	v_mbcnt_hi_u32_b32 v236, -1, v236
	v_and_b32_e32 v236, 16, v236
	v_lshrrev_b32_e32 v234, 1, v236
	v_add_u32_e32 v236, v236, v234
	v_mov_b32_e32 v237, 0
	v_lshl_add_u64 v[234:235], v[160:161], 0, v[236:237]
	v_permlane16_swap_b32_e32 v230, v232
	v_permlane16_swap_b32_e32 v231, v233
	global_store_dwordx4 v[234:235], v[230:233], off offset:64
	s_nop 1

.LBB0_144:
	v_mov_b32_e32 v157, v156
	v_mov_b32_e32 v152, v156
	v_mov_b32_e32 v153, v156
	v_pk_mul_f32 v[158:159], v[12:13], v[152:153]
	v_pk_mul_f32 v[160:161], v[10:11], v[156:157]
	v_pk_mul_f32 v[162:163], v[8:9], v[152:153]
	v_pk_mul_f32 v[164:165], v[6:7], v[156:157]
	v_pk_mul_f32 v[152:153], v[4:5], v[152:153]
	v_pk_mul_f32 v[156:157], v[2:3], v[156:157]
	v_cvt_pk_bf16_f32 v160, v160, v161
	v_cvt_pk_bf16_f32 v161, v158, v159
	v_lshl_add_u64 v[154:155], v[154:155], 0, v[132:133]
	v_cvt_pk_bf16_f32 v158, v164, v165
	v_cvt_pk_bf16_f32 v159, v162, v163
	v_cvt_pk_bf16_f32 v156, v156, v157
	v_cvt_pk_bf16_f32 v157, v152, v153
	flat_store_dwordx2 v[154:155], v[160:161] offset:32
	v_mov_b32_e32 v230, v158
	v_mov_b32_e32 v231, v159
	v_mov_b32_e32 v232, v156
	v_mov_b32_e32 v233, v157
	v_mbcnt_lo_u32_b32 v236, -1, 0
	v_mbcnt_hi_u32_b32 v236, -1, v236
	v_and_b32_e32 v236, 16, v236
	v_lshrrev_b32_e32 v234, 1, v236
	v_add_u32_e32 v236, v236, v234
	v_mov_b32_e32 v237, 0
	v_lshl_add_u64 v[234:235], v[154:155], 0, v[236:237]
	v_permlane16_swap_b32_e32 v230, v232
	v_permlane16_swap_b32_e32 v231, v233
	global_store_dwordx4 v[234:235], v[230:233], off offset:64
	s_nop 1

.LBB0_692:
	v_mov_b32_e32 v164, v162
	v_mov_b32_e32 v165, v162
	v_pk_mul_f32 v[166:167], v[120:121], v[164:165]
	v_pk_mul_f32 v[168:169], v[118:119], v[162:163]
	v_pk_mul_f32 v[164:165], v[116:117], v[164:165]
	v_pk_mul_f32 v[162:163], v[114:115], v[162:163]
	v_mov_b32_e32 v157, v133
	v_cvt_pk_bf16_f32 v168, v168, v169
	v_cvt_pk_bf16_f32 v169, v166, v167
	v_lshl_add_u64 v[166:167], v[160:161], 0, v[156:157]
	v_cvt_pk_bf16_f32 v162, v162, v163
	v_cvt_pk_bf16_f32 v163, v164, v165
	v_mov_b32_e32 v230, v168
	v_mov_b32_e32 v231, v169
	v_mov_b32_e32 v232, v162
	v_mov_b32_e32 v233, v163
	v_mbcnt_lo_u32_b32 v236, -1, 0
	v_mbcnt_hi_u32_b32 v236, -1, v236
	v_and_b32_e32 v236, 16, v236
	v_lshrrev_b32_e32 v234, 1, v236
	v_add_u32_e32 v236, v236, v234
	v_mov_b32_e32 v237, 0
	v_lshl_add_u64 v[234:235], v[166:167], 0, v[236:237]
	v_permlane16_swap_b32_e32 v230, v232
	v_permlane16_swap_b32_e32 v231, v233
	global_store_dwordx4 v[234:235], v[230:233], off offset:64
	s_nop 1

.LBB0_720:
	v_mov_b32_e32 v164, v162
	v_mov_b32_e32 v165, v162
	v_pk_mul_f32 v[166:167], v[104:105], v[164:165]
	v_pk_mul_f32 v[168:169], v[102:103], v[162:163]
	v_pk_mul_f32 v[164:165], v[100:101], v[164:165]
	v_pk_mul_f32 v[162:163], v[98:99], v[162:163]
	v_mov_b32_e32 v157, v133
	v_cvt_pk_bf16_f32 v168, v168, v169
	v_cvt_pk_bf16_f32 v169, v166, v167
	v_lshl_add_u64 v[166:167], v[160:161], 0, v[156:157]
	v_cvt_pk_bf16_f32 v162, v162, v163
	v_cvt_pk_bf16_f32 v163, v164, v165
	v_mov_b32_e32 v230, v168
	v_mov_b32_e32 v231, v169
	v_mov_b32_e32 v232, v162
	v_mov_b32_e32 v233, v163
	v_mbcnt_lo_u32_b32 v236, -1, 0
	v_mbcnt_hi_u32_b32 v236, -1, v236
	v_and_b32_e32 v236, 16, v236
	v_lshrrev_b32_e32 v234, 1, v236
	v_add_u32_e32 v236, v236, v234
	v_mov_b32_e32 v237, 0
	v_lshl_add_u64 v[234:235], v[166:167], 0, v[236:237]
	v_permlane16_swap_b32_e32 v230, v232
	v_permlane16_swap_b32_e32 v231, v233
	global_store_dwordx4 v[234:235], v[230:233], off offset:64
	s_nop 1

.LBB0_748:
	v_mov_b32_e32 v164, v162
	v_mov_b32_e32 v165, v162
	v_pk_mul_f32 v[166:167], v[88:89], v[164:165]
	v_pk_mul_f32 v[168:169], v[86:87], v[162:163]
	v_pk_mul_f32 v[164:165], v[84:85], v[164:165]
	v_pk_mul_f32 v[162:163], v[82:83], v[162:163]
	v_mov_b32_e32 v157, v133
	v_cvt_pk_bf16_f32 v168, v168, v169
	v_cvt_pk_bf16_f32 v169, v166, v167
	v_lshl_add_u64 v[166:167], v[160:161], 0, v[156:157]
	v_cvt_pk_bf16_f32 v162, v162, v163
	v_cvt_pk_bf16_f32 v163, v164, v165
	v_mov_b32_e32 v230, v168
	v_mov_b32_e32 v231, v169
	v_mov_b32_e32 v232, v162
	v_mov_b32_e32 v233, v163
	v_mbcnt_lo_u32_b32 v236, -1, 0
	v_mbcnt_hi_u32_b32 v236, -1, v236
	v_and_b32_e32 v236, 16, v236
	v_lshrrev_b32_e32 v234, 1, v236
	v_add_u32_e32 v236, v236, v234
	v_mov_b32_e32 v237, 0
	v_lshl_add_u64 v[234:235], v[166:167], 0, v[236:237]
	v_permlane16_swap_b32_e32 v230, v232
	v_permlane16_swap_b32_e32 v231, v233
	global_store_dwordx4 v[234:235], v[230:233], off offset:64
	s_nop 1

.LBB0_776:
	v_mov_b32_e32 v164, v162
	v_mov_b32_e32 v165, v162
	v_pk_mul_f32 v[166:167], v[72:73], v[164:165]
	v_pk_mul_f32 v[168:169], v[70:71], v[162:163]
	v_pk_mul_f32 v[164:165], v[68:69], v[164:165]
	v_pk_mul_f32 v[162:163], v[66:67], v[162:163]
	v_mov_b32_e32 v157, v133
	v_cvt_pk_bf16_f32 v168, v168, v169
	v_cvt_pk_bf16_f32 v169, v166, v167
	v_lshl_add_u64 v[166:167], v[160:161], 0, v[156:157]
	v_cvt_pk_bf16_f32 v162, v162, v163
	v_cvt_pk_bf16_f32 v163, v164, v165
	v_mov_b32_e32 v230, v168
	v_mov_b32_e32 v231, v169
	v_mov_b32_e32 v232, v162
	v_mov_b32_e32 v233, v163
	v_mbcnt_lo_u32_b32 v236, -1, 0
	v_mbcnt_hi_u32_b32 v236, -1, v236
	v_and_b32_e32 v236, 16, v236
	v_lshrrev_b32_e32 v234, 1, v236
	v_add_u32_e32 v236, v236, v234
	v_mov_b32_e32 v237, 0
	v_lshl_add_u64 v[234:235], v[166:167], 0, v[236:237]
	v_permlane16_swap_b32_e32 v230, v232
	v_permlane16_swap_b32_e32 v231, v233
	global_store_dwordx4 v[234:235], v[230:233], off offset:64
	s_nop 1

.LBB0_804:
	v_mov_b32_e32 v164, v162
	v_mov_b32_e32 v165, v162
	v_pk_mul_f32 v[166:167], v[56:57], v[164:165]
	v_pk_mul_f32 v[168:169], v[54:55], v[162:163]
	v_pk_mul_f32 v[164:165], v[52:53], v[164:165]
	v_pk_mul_f32 v[162:163], v[50:51], v[162:163]
	v_mov_b32_e32 v157, v133
	v_cvt_pk_bf16_f32 v168, v168, v169
	v_cvt_pk_bf16_f32 v169, v166, v167
	v_lshl_add_u64 v[166:167], v[160:161], 0, v[156:157]
	v_cvt_pk_bf16_f32 v162, v162, v163
	v_cvt_pk_bf16_f32 v163, v164, v165
	v_mov_b32_e32 v230, v168
	v_mov_b32_e32 v231, v169
	v_mov_b32_e32 v232, v162
	v_mov_b32_e32 v233, v163
	v_mbcnt_lo_u32_b32 v236, -1, 0
	v_mbcnt_hi_u32_b32 v236, -1, v236
	v_and_b32_e32 v236, 16, v236
	v_lshrrev_b32_e32 v234, 1, v236
	v_add_u32_e32 v236, v236, v234
	v_mov_b32_e32 v237, 0
	v_lshl_add_u64 v[234:235], v[166:167], 0, v[236:237]
	v_permlane16_swap_b32_e32 v230, v232
	v_permlane16_swap_b32_e32 v231, v233
	global_store_dwordx4 v[234:235], v[230:233], off offset:64
	s_nop 1

.LBB0_832:
	v_mov_b32_e32 v164, v162
	v_mov_b32_e32 v165, v162
	v_pk_mul_f32 v[166:167], v[40:41], v[164:165]
	v_pk_mul_f32 v[168:169], v[38:39], v[162:163]
	v_pk_mul_f32 v[164:165], v[36:37], v[164:165]
	v_pk_mul_f32 v[162:163], v[34:35], v[162:163]
	v_mov_b32_e32 v157, v133
	v_cvt_pk_bf16_f32 v168, v168, v169
	v_cvt_pk_bf16_f32 v169, v166, v167
	v_lshl_add_u64 v[166:167], v[160:161], 0, v[156:157]
	v_cvt_pk_bf16_f32 v162, v162, v163
	v_cvt_pk_bf16_f32 v163, v164, v165
	v_mov_b32_e32 v230, v168
	v_mov_b32_e32 v231, v169
	v_mov_b32_e32 v232, v162
	v_mov_b32_e32 v233, v163
	v_mbcnt_lo_u32_b32 v236, -1, 0
	v_mbcnt_hi_u32_b32 v236, -1, v236
	v_and_b32_e32 v236, 16, v236
	v_lshrrev_b32_e32 v234, 1, v236
	v_add_u32_e32 v236, v236, v234
	v_mov_b32_e32 v237, 0
	v_lshl_add_u64 v[234:235], v[166:167], 0, v[236:237]
	v_permlane16_swap_b32_e32 v230, v232
	v_permlane16_swap_b32_e32 v231, v233
	global_store_dwordx4 v[234:235], v[230:233], off offset:64
	s_nop 1

.LBB0_860:
	v_mov_b32_e32 v164, v162
	v_mov_b32_e32 v165, v162
	v_pk_mul_f32 v[166:167], v[24:25], v[164:165]
	v_pk_mul_f32 v[168:169], v[22:23], v[162:163]
	v_pk_mul_f32 v[164:165], v[20:21], v[164:165]
	v_pk_mul_f32 v[162:163], v[18:19], v[162:163]
	v_mov_b32_e32 v157, v133
	v_cvt_pk_bf16_f32 v168, v168, v169
	v_cvt_pk_bf16_f32 v169, v166, v167
	v_lshl_add_u64 v[166:167], v[160:161], 0, v[156:157]
	v_cvt_pk_bf16_f32 v162, v162, v163
	v_cvt_pk_bf16_f32 v163, v164, v165
	v_mov_b32_e32 v230, v168
	v_mov_b32_e32 v231, v169
	v_mov_b32_e32 v232, v162
	v_mov_b32_e32 v233, v163
	v_mbcnt_lo_u32_b32 v236, -1, 0
	v_mbcnt_hi_u32_b32 v236, -1, v236
	v_and_b32_e32 v236, 16, v236
	v_lshrrev_b32_e32 v234, 1, v236
	v_add_u32_e32 v236, v236, v234
	v_mov_b32_e32 v237, 0
	v_lshl_add_u64 v[234:235], v[166:167], 0, v[236:237]
	v_permlane16_swap_b32_e32 v230, v232
	v_permlane16_swap_b32_e32 v231, v233
	global_store_dwordx4 v[234:235], v[230:233], off offset:64
	s_nop 1

.LBB0_888:
	v_mov_b32_e32 v158, v162
	v_mov_b32_e32 v159, v162
	v_pk_mul_f32 v[164:165], v[8:9], v[158:159]
	v_pk_mul_f32 v[166:167], v[6:7], v[162:163]
	v_pk_mul_f32 v[158:159], v[4:5], v[158:159]
	v_pk_mul_f32 v[162:163], v[2:3], v[162:163]
	v_mov_b32_e32 v157, v133
	v_cvt_pk_bf16_f32 v166, v166, v167
	v_cvt_pk_bf16_f32 v167, v164, v165
	v_lshl_add_u64 v[156:157], v[160:161], 0, v[156:157]
	v_cvt_pk_bf16_f32 v160, v162, v163
	v_cvt_pk_bf16_f32 v161, v158, v159
	v_mov_b32_e32 v230, v166
	v_mov_b32_e32 v231, v167
	v_mov_b32_e32 v232, v160
	v_mov_b32_e32 v233, v161
	v_mbcnt_lo_u32_b32 v236, -1, 0
	v_mbcnt_hi_u32_b32 v236, -1, v236
	v_and_b32_e32 v236, 16, v236
	v_lshrrev_b32_e32 v234, 1, v236
	v_add_u32_e32 v236, v236, v234
	v_mov_b32_e32 v237, 0
	v_lshl_add_u64 v[234:235], v[156:157], 0, v[236:237]
	v_permlane16_swap_b32_e32 v230, v232
	v_permlane16_swap_b32_e32 v231, v233
	global_store_dwordx4 v[234:235], v[230:233], off offset:64
	s_nop 1
